# shared barrier: XCD leaders add to the top-level counter without waiting for the return and every workgroup polls that counter (TOPGEN hop removed)
# speedup vs baseline: 1.0033x; 1.0033x over previous
.Lsbar:
	v_readlane_b32 s99, v242, 11
	v_readlane_b32 s100, v242, 30
	s_add_u32 s101, s98, 1
	s_nop 0
	v_mov_b32_e32 v244, s99
	ds_read_b32 v245, v244
	ds_read_b32 v246, v244 offset:4
	s_lshl_b32 s100, s100, 8
	s_add_u32 s100, s100, 0x1400
	v_mov_b32_e32 v247, s100
	v_mov_b32_e32 v248, 1
	global_atomic_add v249, v247, v248, s[70:71] sc0
	buffer_inv sc1
	s_waitcnt lgkmcnt(0)
	v_mul_lo_u32 v245, v245, s101
	v_mul_lo_u32 v246, v246, s101
	v_mov_b32_e32 v250, 0x3400
	v_mov_b32_e32 v251, s98
	s_mov_b32 s99, 0
	s_waitcnt vmcnt(0)
	v_add_u32_e32 v249, 1, v249
	v_cmp_eq_u32_e32 vcc, v249, v245
	s_cbranch_vccz .Lsbar_poll
	buffer_wbl2 sc1
	s_waitcnt vmcnt(0)
	global_atomic_add v250, v248, s[70:71]
